# loop-head alignment: P1 K-loop and D tile loop heads aligned to 64 bytes
# speedup vs baseline: 1.0190x; 1.0048x over previous
;     DI bool next(int i, pg8::Unit& u) const { if (i > 0 || !valid) return false; u.pm = pm; u.pn = pn; return true; }
; template <class Epi, class Sched, bool ALIGN_EPI = false, bool SP2 = false, bool PRE = false>
; __device__ __forceinline__ void gemm_phase(PG8_LAS unsigned char* lds, const Gemm g, const Sched& S, const Epi& E, const f32x4 (*pre)[2][4][2] = nullptr) {
;     ...
;         const bool has_next = S.next(ui + 1, nxt);
;         const char* nA = has_next ? (const char*)g.A + (size_t)nxt.pm * tstep : cA; const char* nB = has_next ? (const char*)g.Bt + (size_t)nxt.pn * tstep : cB;
;         for (int t = 0; t < nt; t += 2) {
;             const bool last = (t == nt - 2);
;             const char* a1 = cA + (size_t)(t + 1) * kstep;
;             const char* a2 = last ? nA : cA + (size_t)(t + 2) * kstep; const char* b2 = last ? nB : cB + (size_t)(t + 2) * kstep;
;             const char* a3 = a2 + kstep; const char* b3 = b2 + kstep;
;     ...
; #pragma unroll
;         for (int a = 0; a < 2; ++a)
; #pragma unroll
;             for (int b = 0; b < 2; ++b)
; #pragma unroll
;                 for (int m = 0; m < 4; ++m)
; #pragma unroll
;                     for (int n = 0; n < 2; ++n) acc[a][b][m][n] = (f32x4){0.f, 0.f, 0.f, 0.f};
.LBB0_186:
	s_ashr_i32 s85, s84, 31
	s_lshl_b64 s[8:9], s[84:85], 19
	s_add_u32 s86, s14, s8
	s_addc_u32 s87, s15, s9
	s_and_b64 s[8:9], s[22:23], exec
	s_cselect_b32 s1, s87, s5
	s_cselect_b32 s3, s86, s4
	s_ashr_i32 s83, s82, 31
	s_lshl_b64 s[8:9], s[82:83], 19
	s_add_u32 s88, s10, s8
	s_addc_u32 s89, s11, s9
	s_and_b64 s[8:9], s[22:23], exec
	s_cselect_b32 s12, s89, s7
	s_cselect_b32 s16, s88, s6
	s_add_u32 s4, s4, 0x40080
	s_addc_u32 s5, s5, 0
	s_add_u32 s17, s6, 0x100
	v_mov_b32_e32 v2, 0
	s_addc_u32 s18, s7, 0
	s_mov_b32 s19, -2
	v_mov_b32_e32 v3, v2
	v_mov_b32_e32 v4, v2
	v_mov_b32_e32 v5, v2
	v_mov_b32_e32 v6, v2
	v_mov_b32_e32 v7, v2
	v_mov_b32_e32 v8, v2
	v_mov_b32_e32 v9, v2
	v_mov_b32_e32 v18, v2
	v_mov_b32_e32 v19, v2
	v_mov_b32_e32 v20, v2
	v_mov_b32_e32 v21, v2
	v_mov_b32_e32 v22, v2
	v_mov_b32_e32 v23, v2
	v_mov_b32_e32 v24, v2
	v_mov_b32_e32 v25, v2
	v_mov_b32_e32 v34, v2
	v_mov_b32_e32 v35, v2
	v_mov_b32_e32 v36, v2
	v_mov_b32_e32 v37, v2
	v_mov_b32_e32 v38, v2
	v_mov_b32_e32 v39, v2
	v_mov_b32_e32 v40, v2
	v_mov_b32_e32 v41, v2
	v_mov_b32_e32 v50, v2
	v_mov_b32_e32 v51, v2
	v_mov_b32_e32 v52, v2
	v_mov_b32_e32 v53, v2
	v_mov_b32_e32 v54, v2
	v_mov_b32_e32 v55, v2
	v_mov_b32_e32 v56, v2
	v_mov_b32_e32 v57, v2
	v_mov_b32_e32 v10, v2
	v_mov_b32_e32 v11, v2
	v_mov_b32_e32 v12, v2
	v_mov_b32_e32 v13, v2
	v_mov_b32_e32 v14, v2
	v_mov_b32_e32 v15, v2
	v_mov_b32_e32 v16, v2
	v_mov_b32_e32 v17, v2
	v_mov_b32_e32 v26, v2
	v_mov_b32_e32 v27, v2
	v_mov_b32_e32 v28, v2
	v_mov_b32_e32 v29, v2
	v_mov_b32_e32 v30, v2
	v_mov_b32_e32 v31, v2
	v_mov_b32_e32 v32, v2
	v_mov_b32_e32 v33, v2
	v_mov_b32_e32 v42, v2
	v_mov_b32_e32 v43, v2
	v_mov_b32_e32 v44, v2
	v_mov_b32_e32 v45, v2
	v_mov_b32_e32 v46, v2
	v_mov_b32_e32 v47, v2
	v_mov_b32_e32 v48, v2
	v_mov_b32_e32 v49, v2
	v_mov_b32_e32 v58, v2
	v_mov_b32_e32 v59, v2
	v_mov_b32_e32 v60, v2
	v_mov_b32_e32 v61, v2
	v_mov_b32_e32 v62, v2
	v_mov_b32_e32 v63, v2
	v_mov_b32_e32 v64, v2
	v_mov_b32_e32 v65, v2
	v_mov_b32_e32 v66, v2
	v_mov_b32_e32 v67, v2
	v_mov_b32_e32 v68, v2
	v_mov_b32_e32 v69, v2
	v_mov_b32_e32 v70, v2
	v_mov_b32_e32 v71, v2
	v_mov_b32_e32 v72, v2
	v_mov_b32_e32 v73, v2
	v_mov_b32_e32 v82, v2
	v_mov_b32_e32 v83, v2
	v_mov_b32_e32 v84, v2
	v_mov_b32_e32 v85, v2
	v_mov_b32_e32 v86, v2
	v_mov_b32_e32 v87, v2
	v_mov_b32_e32 v88, v2
	v_mov_b32_e32 v89, v2
	v_mov_b32_e32 v98, v2
	v_mov_b32_e32 v99, v2
	v_mov_b32_e32 v100, v2
	v_mov_b32_e32 v101, v2
	v_mov_b32_e32 v102, v2
	v_mov_b32_e32 v103, v2
	v_mov_b32_e32 v104, v2
	v_mov_b32_e32 v105, v2
	v_mov_b32_e32 v114, v2
	v_mov_b32_e32 v115, v2
	v_mov_b32_e32 v116, v2
	v_mov_b32_e32 v117, v2
	v_mov_b32_e32 v118, v2
	v_mov_b32_e32 v119, v2
	v_mov_b32_e32 v120, v2
	v_mov_b32_e32 v121, v2
	v_mov_b32_e32 v74, v2
	v_mov_b32_e32 v75, v2
	v_mov_b32_e32 v76, v2
	v_mov_b32_e32 v77, v2
	v_mov_b32_e32 v78, v2
	v_mov_b32_e32 v79, v2
	v_mov_b32_e32 v80, v2
	v_mov_b32_e32 v81, v2
	v_mov_b32_e32 v90, v2
	v_mov_b32_e32 v91, v2
	v_mov_b32_e32 v92, v2
	v_mov_b32_e32 v93, v2
	v_mov_b32_e32 v94, v2
	v_mov_b32_e32 v95, v2
	v_mov_b32_e32 v96, v2
	v_mov_b32_e32 v97, v2
	v_mov_b32_e32 v106, v2
	v_mov_b32_e32 v107, v2
	v_mov_b32_e32 v108, v2
	v_mov_b32_e32 v109, v2
	v_mov_b32_e32 v110, v2
	v_mov_b32_e32 v111, v2
	v_mov_b32_e32 v112, v2
	v_mov_b32_e32 v113, v2
	v_mov_b32_e32 v122, v2
	v_mov_b32_e32 v123, v2
	v_mov_b32_e32 v124, v2
	v_mov_b32_e32 v125, v2
	v_mov_b32_e32 v126, v2
	v_mov_b32_e32 v127, v2
	v_mov_b32_e32 v128, v2
	v_mov_b32_e32 v129, v2
	.p2align 6

; template <bool MASKED>
; DI void attn_tile_sw(int MODE, LAS const unsigned char* kst, LAS const unsigned char* vst, const bf16x8 (&qf)[4], float bstep, float ca, int lane, f32x16& o0, f32x16& o1, float& m, float& l) {
;     ...
;     f32x16 s; { const float sb = bstep * (float)(4 * hh - qq);
; #pragma unroll
;         for (int i = 0; i < 16; ++i) s[i] = bstep * (float)((i & 3) + 8 * (i >> 2)) + sb; }
; DI void unit_dilated2(int u, const bf16* __restrict__ Q, const bf16* __restrict__ K, const bf16* __restrict__ V, const bf16* __restrict__ G, bf16* __restrict__ MIX, LAS unsigned char* lds, int tid, int lane, int wave) {
;     ...
;     for (int seq = 0; seq < 6; ++seq) {
;         const DilWT nw = dil_wt(seq < 5 ? seq + 1 : 5, wave, b, h, T0, qq, slope2);
;         bf16x8 qn[4];
; #pragma unroll
;         for (int st = 0; st < 4; ++st) qn[st] = *(const bf16x8*)(Q + nw.qrow * 512 + h * 64 + 16 * st + 8 * hh);
;         f32x16 o0, o1;
; #pragma unroll
;         for (int i = 0; i < 16; ++i) { o0[i] = 0.f; o1[i] = 0.f; }
;         float m = NEG, l = 0.f;
; #pragma unroll 1
;         for (int a = 4; a >= cw.a0; --a) {
;             dil_store(kst, vst, kr, vr, lane);
;             if (a > cw.a0) dil_load(kr, vr, K, V, cw.rb0 + (long)(32 * (a - 1)) * cw.gstride, cw.gstride, lane);
;             else if (seq < 5) dil_load(kr, vr, K, V, nw.rb0 + (long)(32 * 4) * nw.gstride, nw.gstride, lane);
;             const float ca = -cw.bstep * (float)(128 - 32 * a);
.LBB0_755:
	s_mov_b32 s35, s44
	s_add_i32 s44, s44, 1
	s_cmp_lg_u32 s35, 5
	s_cselect_b64 s[22:23], -1, 0
	s_and_b64 s[0:1], s[22:23], exec
	s_cselect_b32 s0, s44, 5
	s_lshl_b32 s1, s0, 3
	s_and_b32 s1, s1, 8
	s_and_b32 s0, s0, 14
	s_add_i32 s1, s1, s33
	s_sub_i32 s8, 4, s0
	s_mov_b64 s[2:3], s[16:17]
	s_lshr_b32 s16, s1, s8
	s_lshr_b32 s8, 16, s0
	s_add_i32 s8, s8, -1
	s_and_b32 s1, s1, s8
	s_lshl_b32 s9, s1, 5
	v_or_b32_e32 v3, s9, v228
	v_lshlrev_b32_e32 v3, s0, v3
	v_mov_b32_e32 v241, v184
	v_add_u32_e32 v184, s16, v3
	v_ashrrev_i32_e32 v185, 31, v184
	v_lshl_add_u64 v[4:5], s[10:11], 0, v[184:185]
	v_lshlrev_b64 v[4:5], 10, v[4:5]
	s_waitcnt vmcnt(0)
	v_mov_b64_e32 v[164:165], v[132:133]
	v_mov_b64_e32 v[168:169], v[124:125]
	v_mov_b64_e32 v[172:173], v[120:121]
	v_mov_b64_e32 v[176:177], v[116:117]
	v_lshl_add_u64 v[4:5], v[196:197], 0, v[4:5]
	v_mov_b64_e32 v[162:163], v[130:131]
	v_mov_b64_e32 v[166:167], v[122:123]
	v_mov_b64_e32 v[170:171], v[118:119]
	v_mov_b64_e32 v[174:175], v[114:115]
	global_load_dwordx4 v[114:117], v[4:5], off
	global_load_dwordx4 v[118:121], v[4:5], off offset:32
	global_load_dwordx4 v[122:125], v[4:5], off offset:64
	global_load_dwordx4 v[130:133], v[4:5], off offset:96
	s_lshr_b32 s8, s34, s0
	s_add_i32 s1, s9, s8
	s_add_i32 s8, s1, 0xffffff80
	s_ashr_i32 s9, s8, 31
	s_lshl_b32 s38, 0x200, s0
	s_lshl_b64 s[8:9], s[8:9], s0
	s_add_u32 s16, s12, s16
	s_addc_u32 s17, s13, 0
	s_add_u32 s8, s16, s8
	s_addc_u32 s9, s17, s9
	s_lshl_b64 s[8:9], s[8:9], 9
	s_or_b64 s[16:17], s[8:9], s[14:15]
	s_mov_b64 s[20:21], s[18:19]
	s_mov_b64 s[18:19], s[38:39]
	s_lshl_b32 s38, s38, 7
	s_add_i32 s8, s0, 9
	s_sub_u32 s9, s80, s76
	v_lshlrev_b32_e32 v4, s8, v186
	v_lshlrev_b32_e32 v5, s8, v190
	v_lshlrev_b32_e32 v6, s8, v192
	v_lshlrev_b32_e32 v7, s8, v194
	v_add_lshl_u32 v200, v4, v188, 1
	v_add_lshl_u32 v201, v5, v188, 1
	v_add_lshl_u32 v202, v6, v188, 1
	v_add_lshl_u32 v203, v7, v188, 1
	v_add_u32_e32 v204, s9, v200
	v_add_u32_e32 v205, s9, v201
	v_add_u32_e32 v206, s9, v202
	v_add_u32_e32 v207, s9, v203
	v_mul_lo_u32 v216, s20, v186
	s_mul_i32 s8, s20, 0x60
	s_add_u32 s8, s2, s8
	s_addc_u32 s9, s3, 0
	s_lshl_b64 s[8:9], s[8:9], 1
	s_add_u32 s8, s8, s76
	s_addc_u32 s9, s9, s77
	s_sub_u32 s3, s80, s76
	s_lshl_b32 s2, s20, 4
	v_add_lshl_u32 v216, v216, v188, 1
	v_add_u32_e32 v217, s2, v216
	v_add_u32_e32 v218, s2, v217
	v_add_u32_e32 v219, s2, v218
	v_add_u32_e32 v220, s3, v216
	v_add_u32_e32 v221, s3, v217
	v_add_u32_e32 v222, s3, v218
	v_add_u32_e32 v223, s3, v219
	v_mul_f32_e32 v4, v199, v231
	v_mul_f32_e32 v198, 0, v199
	v_mov_b32_e32 v6, v199
	v_mov_b32_e32 v16, v2
	v_mov_b32_e32 v17, v2
	v_pk_add_f32 v[18:19], v[198:199], v[4:5] op_sel_hi:[1,0]
	v_pk_fma_f32 v[20:21], v[6:7], s[96:97], v[4:5] op_sel_hi:[0,1,0]
	v_pk_fma_f32 v[22:23], v[6:7], s[74:75], v[4:5] op_sel_hi:[0,1,0]
	v_pk_fma_f32 v[24:25], v[6:7], s[82:83], v[4:5] op_sel_hi:[0,1,0]
	v_pk_fma_f32 v[26:27], v[6:7], s[86:87], v[4:5] op_sel_hi:[0,1,0]
	v_pk_fma_f32 v[28:29], v[6:7], s[90:91], v[4:5] op_sel_hi:[0,1,0]
	v_pk_fma_f32 v[30:31], v[6:7], s[68:69], v[4:5] op_sel_hi:[0,1,0]
	v_pk_fma_f32 v[32:33], v[6:7], s[70:71], v[4:5] op_sel_hi:[0,1,0]
	s_lshl_b32 s2, s20, 6
	s_mov_b32 s31, 4
	s_mov_b32 s51, 0
	v_mov_b32_e32 v198, 0xf149f2ca
	v_mov_b32_e32 v185, 0
	.p2align 6
